# w24 + K-tile 1 staged before the first prologue wait in all four GEMM prologues (vmcnt 2 -> 8) + fl_phase-done signal moved after the second prologue barrier
# baseline (speedup 1.0000x reference)
; #define PG8_STAGE(bufoff, gbase, voff) do { _Pragma("unroll") for (int _i = 0; _i < 2; ++_i) \
;         __builtin_amdgcn_global_load_lds((const unsigned*)((const char*)(gbase) + (voff)[_i]), (PG8_LAS unsigned*)(lds + (bufoff) + ldsw + _i * 8192), 16, 0, 0); } while (0)
; #define PG8_WAIT_V(n) asm volatile("s_waitcnt vmcnt(" #n ")" ::: "memory")
; #define PG8_BAR __builtin_amdgcn_s_barrier()
; template <class Epi, class Sched, bool ALIGN_EPI = false, bool SP2 = false>
; __device__ __forceinline__ void gemm_phase(PG8_LAS unsigned char* lds, const Gemm g, const Sched& S, const Epi& E) {
;     ...
;         PG8_STAGE(PG8_SB(0, 0), cB, voffB); PG8_STAGE(PG8_SB(0, 1), cB + hstep, voffB); PG8_STAGE(PG8_SA(0, 0), cA, voffA); PG8_STAGE(PG8_SA(0, 1), cA + hstep, voffA);
;         if (wr == 1) PG8_BAR;
;         PG8_WAIT_V(2); PG8_BAR;
;         PG8_STAGE(PG8_SB(1, 0), cB + kstep, voffB); PG8_STAGE(PG8_SA(1, 0), cA + kstep, voffA); PG8_STAGE(PG8_SB(1, 1), cB + hstep + kstep, voffB);
;         PG8_WAIT_V(6); PG8_BAR;
.LBB0_151:
	s_lshl_b32 s15, s17, 5
	s_mov_b64 s[22:23], 0x80
	s_and_b32 s15, s15, 0x60
	s_add_i32 m0, s75, 0x18000
	v_lshl_add_u64 v[6:7], v[6:7], 0, s[22:23]
	s_lshl_b32 s14, s16, 13
	s_lshl_b32 s17, s15, 7
	global_load_lds_dwordx4 v[6:7], off
	v_lshl_add_u64 v[4:5], v[4:5], 0, s[22:23]
	s_add_i32 m0, s75, 0x1a000
	s_add_i32 s92, s75, 0x8000
	s_add_i32 s93, s75, 0xa000
	global_load_lds_dwordx4 v[4:5], off
	v_lshl_add_u64 v[0:1], v[0:1], 0, s[22:23]
	s_mov_b32 m0, s92
	s_add_u32 s36, s84, 0x40080
	global_load_lds_dwordx4 v[0:1], off
	v_lshl_add_u64 v[0:1], v[2:3], 0, s[22:23]
	s_mov_b32 m0, s93
	s_addc_u32 s37, s85, 0
	global_load_lds_dwordx4 v[0:1], off
	s_add_i32 m0, s75, 0x1c000
	v_lshl_add_u64 v[0:1], s[36:37], 0, v[132:133]
	global_load_lds_dwordx4 v[0:1], off
	v_lshl_add_u64 v[0:1], s[36:37], 0, v[128:129]
	s_add_i32 m0, s75, 0x1e000
	s_cmpk_lt_u32 s5, 0x100
	global_load_lds_dwordx4 v[0:1], off
	s_waitcnt vmcnt(8)
	s_barrier
	v_lshrrev_b32_e32 v1, 1, v9
	v_and_b32_e32 v1, 24, v1
	v_and_b32_e32 v0, 15, v9
	v_lshlrev_b32_e32 v2, 1, v1
	v_lshl_or_b32 v146, s16, 6, v0
	v_lshl_or_b32 v0, v0, 6, v2
	v_lshlrev_b32_e32 v2, 2, v9
	v_and_b32_e32 v2, 32, v2
	v_bitop3_b32 v3, v0, s14, v2 bitop3:0xde
	v_bitop3_b32 v147, v0, s17, v2 bitop3:0xde
	v_lshlrev_b32_e32 v0, 14, v13
	v_and_b32_e32 v0, 0xffff8000, v0
	v_or_b32_e32 v148, s15, v1
	v_lshl_add_u32 v0, v12, 11, v0
	v_and_b32_e32 v1, 1, v13
	v_lshl_or_b32 v0, v1, 6, v0
	v_lshl_add_u32 v136, v14, 1, v0
	v_lshlrev_b32_e32 v0, 14, v8
	v_and_b32_e32 v0, 0xffff8000, v0
	s_waitcnt vmcnt(6)
	v_lshl_add_u32 v0, v10, 11, v0
	v_and_b32_e32 v1, 1, v8
	s_cselect_b64 s[38:39], -1, 0
	v_lshl_or_b32 v0, v1, 6, v0
	s_add_i32 s94, 0, 0x10000
	s_add_i32 s95, 0, 0x14000
	s_sext_i32_i8 s97, s18
	v_mov_b32_e32 v137, v133
	v_lshl_add_u32 v138, v11, 1, v0
	v_mov_b32_e32 v139, v133
	v_mov_b64_e32 v[140:141], 0x300
	v_mov_b64_e32 v[142:143], 0x2ff
	s_mov_b64 s[40:41], 0x100
	v_add_u32_e32 v149, s94, v147
	v_add_u32_e32 v150, s95, v147
	v_add_u32_e32 v151, 0, v3
	s_movk_i32 s96, 0x1800
	s_barrier
	s_mov_b32 s100, 0
	s_branch .LBB0_154

; #define PG8_STAGE(bufoff, gbase, voff) do { _Pragma("unroll") for (int _i = 0; _i < 2; ++_i) \
;         __builtin_amdgcn_global_load_lds((const unsigned*)((const char*)(gbase) + (voff)[_i]), (PG8_LAS unsigned*)(lds + (bufoff) + ldsw + _i * 8192), 16, 0, 0); } while (0)
; #define PG8_WAIT_V(n) asm volatile("s_waitcnt vmcnt(" #n ")" ::: "memory")
; #define PG8_BAR __builtin_amdgcn_s_barrier()
; template <class Epi, class Sched, bool ALIGN_EPI = false, bool SP2 = false>
; __device__ __forceinline__ void gemm_phase(PG8_LAS unsigned char* lds, const Gemm g, const Sched& S, const Epi& E) {
;     ...
;         PG8_STAGE(PG8_SB(0, 0), cB, voffB); PG8_STAGE(PG8_SB(0, 1), cB + hstep, voffB); PG8_STAGE(PG8_SA(0, 0), cA, voffA); PG8_STAGE(PG8_SA(0, 1), cA + hstep, voffA);
;         if (wr == 1) PG8_BAR;
;         PG8_WAIT_V(2); PG8_BAR;
;         PG8_STAGE(PG8_SB(1, 0), cB + kstep, voffB); PG8_STAGE(PG8_SA(1, 0), cA + kstep, voffA); PG8_STAGE(PG8_SB(1, 1), cB + hstep + kstep, voffB);
;         PG8_WAIT_V(6); PG8_BAR;
.LBB0_532:
	s_add_u32 s81, s10, 0x22000
	s_addc_u32 s82, s11, 0
	s_add_u32 s40, s72, 0x1000
	s_addc_u32 s41, s73, 0
	v_bfe_u32 v16, v11, 4, 2
	s_add_u32 s83, s10, 0x27000
	v_and_b32_e32 v15, 15, v11
	v_lshlrev_b32_e32 v17, 4, v16
	v_lshlrev_b32_e32 v11, 2, v11
	s_addc_u32 s84, s11, 0
	v_lshl_or_b32 v218, s17, 6, v15
	v_lshl_or_b32 v15, v15, 6, v17
	s_lshl_b32 s14, s17, 13
	v_and_b32_e32 v11, 32, v11
	v_bitop3_b32 v17, v15, s14, v11 bitop3:0xde
	s_lshl_b32 s14, s18, 5
	s_mov_b64 s[44:45], 0x80
	s_and_b32 s17, s14, 0x60
	s_add_i32 m0, s57, 0x18000
	v_lshl_add_u64 v[6:7], v[6:7], 0, s[44:45]
	s_lshl_b32 s14, s17, 7
	global_load_lds_dwordx4 v[6:7], off
	v_lshl_add_u64 v[4:5], v[4:5], 0, s[44:45]
	s_add_i32 m0, s57, 0x1a000
	s_add_i32 s85, s57, 0x8000
	s_add_i32 s86, s57, 0xa000
	v_bitop3_b32 v219, v15, s14, v11 bitop3:0xde
	global_load_lds_dwordx4 v[4:5], off
	v_lshl_add_u64 v[0:1], v[0:1], 0, s[44:45]
	s_mov_b32 m0, s85
	s_add_u32 s14, s76, 0x40080
	global_load_lds_dwordx4 v[0:1], off
	v_lshl_add_u64 v[0:1], v[2:3], 0, s[44:45]
	s_mov_b32 m0, s86
	s_addc_u32 s15, s77, 0
	global_load_lds_dwordx4 v[0:1], off
	s_add_i32 m0, s57, 0x1c000
	v_lshl_add_u64 v[0:1], s[14:15], 0, v[166:167]
	global_load_lds_dwordx4 v[0:1], off
	v_lshl_add_u64 v[0:1], s[14:15], 0, v[170:171]
	s_add_i32 m0, s57, 0x1e000
	s_cmpk_lt_u32 s16, 0x100
	global_load_lds_dwordx4 v[0:1], off
	s_waitcnt vmcnt(8)
	s_barrier
	v_lshlrev_b32_e32 v0, 14, v8
	v_and_b32_e32 v0, 0xffff8000, v0
	v_lshl_add_u32 v0, v9, 11, v0
	v_and_b32_e32 v1, 1, v8
	v_lshl_or_b32 v0, v1, 6, v0
	v_lshl_add_u32 v172, v10, 1, v0
	v_lshlrev_b32_e32 v0, 14, v12
	v_and_b32_e32 v0, 0xffff8000, v0
	s_waitcnt vmcnt(6)
	v_lshl_add_u32 v0, v13, 11, v0
	v_and_b32_e32 v1, 1, v12
	s_cselect_b64 s[46:47], -1, 0
	v_lshl_or_b32 v0, v1, 6, v0
	s_add_i32 s87, 0, 0x10000
	s_add_i32 s88, 0, 0x14000
	v_cmp_eq_u32_e64 s[36:37], 0, v16
	v_lshl_or_b32 v220, v16, 3, s17
	v_mov_b32_e32 v173, v167
	v_lshl_add_u32 v174, v14, 1, v0
	v_mov_b32_e32 v175, v167
	v_mov_b64_e32 v[176:177], 0x100
	v_mov_b64_e32 v[178:179], 0xff
	v_add_u32_e32 v221, s87, v219
	v_add_u32_e32 v222, s88, v219
	v_add_u32_e32 v223, 0, v17
	s_barrier
	s_branch .LBB0_535

; #define PG8_STAGE(bufoff, gbase, voff) do { _Pragma("unroll") for (int _i = 0; _i < 2; ++_i) \
;         __builtin_amdgcn_global_load_lds((const unsigned*)((const char*)(gbase) + (voff)[_i]), (PG8_LAS unsigned*)(lds + (bufoff) + ldsw + _i * 8192), 16, 0, 0); } while (0)
; #define PG8_WAIT_V(n) asm volatile("s_waitcnt vmcnt(" #n ")" ::: "memory")
; #define PG8_BAR __builtin_amdgcn_s_barrier()
; template <class Epi, class Sched, bool ALIGN_EPI = false, bool SP2 = false>
; __device__ __forceinline__ void gemm_phase(PG8_LAS unsigned char* lds, const Gemm g, const Sched& S, const Epi& E) {
;     ...
;         PG8_STAGE(PG8_SB(0, 0), cB, voffB); PG8_STAGE(PG8_SB(0, 1), cB + hstep, voffB); PG8_STAGE(PG8_SA(0, 0), cA, voffA); PG8_STAGE(PG8_SA(0, 1), cA + hstep, voffA);
;         if (wr == 1) PG8_BAR;
;         PG8_WAIT_V(2); PG8_BAR;
;         PG8_STAGE(PG8_SB(1, 0), cB + kstep, voffB); PG8_STAGE(PG8_SA(1, 0), cA + kstep, voffA); PG8_STAGE(PG8_SB(1, 1), cB + hstep + kstep, voffB);
;         PG8_WAIT_V(6); PG8_BAR;
.LBB0_627:
	s_mov_b64 s[46:47], 0x80
	s_and_b32 s77, s17, 3
	s_add_i32 m0, s61, 0x18000
	v_lshl_add_u64 v[6:7], v[6:7], 0, s[46:47]
	s_lshl_b32 s17, s18, 13
	s_lshl_b32 s19, s77, 5
	s_lshl_b32 s24, s77, 12
	global_load_lds_dwordx4 v[6:7], off
	v_lshl_add_u64 v[2:3], v[2:3], 0, s[46:47]
	s_add_i32 m0, s61, 0x1a000
	s_add_i32 s78, s61, 0x8000
	s_add_i32 s79, s61, 0xa000
	global_load_lds_dwordx4 v[2:3], off
	v_lshl_add_u64 v[0:1], v[0:1], 0, s[46:47]
	s_mov_b32 m0, s78
	s_add_u32 s14, s40, 0x40080
	global_load_lds_dwordx4 v[0:1], off
	v_lshl_add_u64 v[0:1], v[4:5], 0, s[46:47]
	s_mov_b32 m0, s79
	s_addc_u32 s15, s41, 0
	global_load_lds_dwordx4 v[0:1], off
	s_add_i32 m0, s61, 0x1c000
	v_lshl_add_u64 v[0:1], s[14:15], 0, v[162:163]
	global_load_lds_dwordx4 v[0:1], off
	v_lshl_add_u64 v[0:1], s[14:15], 0, v[166:167]
	s_add_i32 m0, s61, 0x1e000
	s_cmpk_lt_u32 s16, 0x100
	global_load_lds_dwordx4 v[0:1], off
	s_waitcnt vmcnt(8)
	s_barrier
	v_lshrrev_b32_e32 v1, 1, v8
	v_and_b32_e32 v170, 24, v1
	v_and_b32_e32 v0, 15, v8
	v_lshlrev_b32_e32 v1, 1, v170
	v_lshl_or_b32 v171, s18, 6, v0
	v_lshl_or_b32 v0, v0, 6, v1
	v_lshlrev_b32_e32 v1, 2, v8
	v_and_b32_e32 v1, 32, v1
	v_bitop3_b32 v2, v0, s17, v1 bitop3:0xde
	v_bitop3_b32 v197, v0, s24, v1 bitop3:0xde
	v_lshlrev_b32_e32 v0, 14, v9
	v_and_b32_e32 v0, 0xffff8000, v0
	v_lshl_add_u32 v0, v10, 11, v0
	v_and_b32_e32 v1, 1, v9
	v_lshl_or_b32 v0, v1, 6, v0
	v_lshl_add_u32 v176, v11, 1, v0
	v_lshlrev_b32_e32 v0, 14, v12
	v_and_b32_e32 v0, 0xffff8000, v0
	s_waitcnt vmcnt(6)
	v_lshl_add_u32 v0, v13, 11, v0
	v_and_b32_e32 v1, 1, v12
	s_cselect_b64 s[48:49], -1, 0
	v_lshlrev_b32_e32 v168, 2, v170
	v_lshl_or_b32 v0, v1, 6, v0
	s_add_i32 s80, 0, 0x10000
	s_add_i32 s81, 0, 0x14000
	v_lshl_add_u64 v[172:173], s[64:65], 0, v[168:169]
	v_lshl_add_u64 v[174:175], s[62:63], 0, v[168:169]
	v_mov_b32_e32 v177, v169
	v_lshl_add_u32 v178, v14, 1, v0
	v_mov_b32_e32 v179, v169
	v_mov_b64_e32 v[180:181], 0x400
	v_mov_b64_e32 v[182:183], 0x3ff
	v_add_u32_e32 v198, s80, v197
	v_add_u32_e32 v199, s81, v197
	v_add_u32_e32 v200, 0, v2
	s_mov_b32 s50, 0x3e38aa3b
	s_lshl_b32 s82, s19, 2
	v_lshlrev_b32_e32 v168, 2, v170
	v_mov_b32_e32 v201, 0x358637bd
	s_barrier
	s_and_saveexec_b64 s[100:101], s[92:93]
	s_cbranch_execz .Lp8_sig_done
	v_mov_b32_e32 v250, 0
	v_mov_b32_e32 v251, 1
	global_atomic_add v250, v251, s[10:11] offset:3072
.Lp8_sig_done:
	s_mov_b64 exec, s[100:101]
	s_mov_b32 s100, 0
	s_branch .LBB0_630

; #define PG8_STAGE(bufoff, gbase, voff) do { _Pragma("unroll") for (int _i = 0; _i < 2; ++_i) \
;         __builtin_amdgcn_global_load_lds((const unsigned*)((const char*)(gbase) + (voff)[_i]), (PG8_LAS unsigned*)(lds + (bufoff) + ldsw + _i * 8192), 16, 0, 0); } while (0)
; #define PG8_WAIT_V(n) asm volatile("s_waitcnt vmcnt(" #n ")" ::: "memory")
; #define PG8_BAR __builtin_amdgcn_s_barrier()
; template <class Epi, class Sched, bool ALIGN_EPI = false, bool SP2 = false>
; __device__ __forceinline__ void gemm_phase(PG8_LAS unsigned char* lds, const Gemm g, const Sched& S, const Epi& E) {
;     ...
;         PG8_STAGE(PG8_SB(0, 0), cB, voffB); PG8_STAGE(PG8_SB(0, 1), cB + hstep, voffB); PG8_STAGE(PG8_SA(0, 0), cA, voffA); PG8_STAGE(PG8_SA(0, 1), cA + hstep, voffA);
;         if (wr == 1) PG8_BAR;
;         PG8_WAIT_V(2); PG8_BAR;
;         PG8_STAGE(PG8_SB(1, 0), cB + kstep, voffB); PG8_STAGE(PG8_SA(1, 0), cA + kstep, voffA); PG8_STAGE(PG8_SB(1, 1), cB + hstep + kstep, voffB);
;         PG8_WAIT_V(6); PG8_BAR;
.LBB0_986:
	s_add_u32 s46, s10, 0x28000
	s_addc_u32 s47, s11, 0
	s_lshl_b32 s10, s15, 5
	s_and_b32 s19, s10, 0x60
	s_mov_b64 s[10:11], 0x80
	s_add_i32 m0, s35, 0x18000
	v_lshl_add_u64 v[6:7], v[6:7], 0, s[10:11]
	s_lshl_b32 s18, s1, 13
	s_lshl_b32 s15, s19, 7
	global_load_lds_dwordx4 v[6:7], off
	v_lshl_add_u64 v[4:5], v[4:5], 0, s[10:11]
	s_add_i32 m0, s35, 0x1a000
	s_add_i32 s48, s35, 0x8000
	s_add_i32 s49, s35, 0xa000
	global_load_lds_dwordx4 v[4:5], off
	v_lshl_add_u64 v[0:1], v[0:1], 0, s[10:11]
	s_mov_b32 m0, s48
	s_add_u32 s16, s38, 0x40080
	global_load_lds_dwordx4 v[0:1], off
	v_lshl_add_u64 v[0:1], v[2:3], 0, s[10:11]
	s_mov_b32 m0, s49
	s_addc_u32 s17, s39, 0
	global_load_lds_dwordx4 v[0:1], off
	s_add_i32 m0, s35, 0x1c000
	v_lshl_add_u64 v[0:1], s[16:17], 0, v[146:147]
	global_load_lds_dwordx4 v[0:1], off
	v_lshl_add_u64 v[0:1], s[16:17], 0, v[150:151]
	s_add_i32 m0, s35, 0x1e000
	s_cmpk_lt_u32 s14, 0x100
	global_load_lds_dwordx4 v[0:1], off
	s_waitcnt vmcnt(8)
	s_barrier
	v_lshrrev_b32_e32 v1, 1, v216
	v_and_b32_e32 v1, 24, v1
	v_and_b32_e32 v0, 15, v216
	v_lshlrev_b32_e32 v2, 1, v1
	v_lshl_or_b32 v162, s1, 6, v0
	v_lshl_or_b32 v0, v0, 6, v2
	v_lshlrev_b32_e32 v2, 2, v216
	v_and_b32_e32 v2, 32, v2
	v_bitop3_b32 v3, v0, s18, v2 bitop3:0xde
	v_bitop3_b32 v163, v0, s15, v2 bitop3:0xde
	v_lshlrev_b32_e32 v0, 14, v8
	v_and_b32_e32 v0, 0xffff8000, v0
	v_or_b32_e32 v164, s19, v1
	v_lshl_add_u32 v0, v9, 11, v0
	v_and_b32_e32 v1, 1, v8
	v_lshl_or_b32 v0, v1, 6, v0
	v_lshl_add_u32 v152, v10, 1, v0
	v_lshlrev_b32_e32 v0, 14, v11
	v_and_b32_e32 v0, 0xffff8000, v0
	s_waitcnt vmcnt(6)
	v_lshl_add_u32 v0, v12, 11, v0
	v_and_b32_e32 v1, 1, v11
	s_cselect_b64 s[14:15], -1, 0
	v_lshl_or_b32 v0, v1, 6, v0
	s_add_i32 s50, 0, 0x10000
	s_add_i32 s51, 0, 0x14000
	s_sext_i32_i8 s56, s0
	v_mov_b32_e32 v153, v147
	v_lshl_add_u32 v154, v13, 1, v0
	v_mov_b32_e32 v155, v147
	v_mov_b64_e32 v[156:157], 0x100
	v_mov_b64_e32 v[158:159], 0xff
	v_add_u32_e32 v165, s50, v163
	v_add_u32_e32 v166, s51, v163
	v_add_u32_e32 v167, 0, v3
	s_mov_b64 s[16:17], 0x80000
	s_mov_b32 s52, 0x80000
	s_mov_b64 s[18:19], 0x90000
	s_mov_b32 s53, 0x90000
	s_mov_b64 s[20:21], 0xa0000
	s_mov_b32 s54, 0xa0000
	s_mov_b64 s[22:23], 0xb0000
	s_mov_b32 s55, 0xb0000
	s_barrier
	s_branch .LBB0_989
